# diff-attention tile loop: half-step stagger of waves 4-7 (mid barrier, V DMA moved to PV phase)
# speedup vs baseline: 1.0449x; 1.0449x over previous
.LBB0_423:
	s_lshl_b64 s[56:57], s[54:55], 1
	s_and_b32 s56, s56, 0xffffff00
	s_bitcmp0_b32 s82, 0
	s_cselect_b32 s25, s73, s72
	s_lshl_b32 s0, s25, 11
	s_or_b32 s0, s48, s0
	s_mov_b32 s1, s49
	s_lshl_b64 s[6:7], s[0:1], 1
	s_add_u32 s0, s74, s6
	s_addc_u32 s1, s75, s7
	s_lshl_b32 s2, s82, 7
	s_and_b32 s2, s2, 0x100
	s_add_u32 s4, s0, s2
	v_readlane_b32 s0, v255, 11
	s_addc_u32 s5, s1, 0
	v_mbcnt_lo_u32_b32 v0, -1, 0
	v_mbcnt_hi_u32_b32 v0, -1, v0
	s_mov_b32 s1, s97
	v_add_u32_e32 v14, s0, v0
	v_readlane_b32 s0, v255, 2
	s_add_u32 s10, s76, s2
	s_addc_u32 s11, s77, 0
	v_readfirstlane_b32 s21, v14
	v_bfe_u32 v18, v14, 4, 2
	s_ashr_i32 s29, s21, 6
	v_bitop3_b32 v0, v18, v14, 15 bitop3:0x78
	v_lshl_or_b32 v2, s29, 3, v18
	v_lshlrev_b32_e32 v19, 3, v0
	v_and_b32_e32 v3, 15, v14
	v_lshl_or_b32 v0, v2, 12, v19
	v_or_b32_e32 v2, 4, v2
	v_bitop3_b32 v3, v2, v3, 7 bitop3:0x6c
	v_lshlrev_b32_e32 v20, 3, v3
	s_lshl_b32 s0, s29, 4
	v_bfe_u32 v3, v14, 2, 3
	v_bitop3_b32 v21, s0, 51, v3 bitop3:0xc8
	s_ashr_i32 s0, s21, 1
	v_lshlrev_b32_e32 v4, 3, v14
	v_lshrrev_b32_e32 v3, 1, v14
	s_and_b32 s33, s0, 0xffffff80
	v_and_b32_e32 v22, 24, v4
	v_and_b32_e32 v23, 32, v14
	v_and_or_b32 v3, v3, 8, v21
	v_or3_b32 v5, s33, v22, v23
	v_lshlrev_b32_e32 v3, 12, v3
	v_or_b32_e32 v7, 64, v5
	s_lshl_b32 s0, s29, 11
	v_add_u32_e32 v4, v3, v5
	v_add_u32_e32 v6, v3, v7
	v_or_b32_e32 v3, 0x4000, v3
	s_add_i32 s0, s0, 0
	v_lshl_or_b32 v2, v2, 12, v20
	v_add_u32_e32 v8, v3, v5
	v_add_u32_e32 v10, v3, v7
	s_add_i32 s2, s0, 0x10000
	v_mov_b32_e32 v3, v1
	s_lshl_b32 s3, s29, 12
	v_lshl_add_u64 v[12:13], v[0:1], 1, s[10:11]
	s_mov_b32 m0, s2
	v_lshl_add_u64 v[2:3], v[2:3], 1, s[10:11]
	s_add_i32 s10, s0, 0x10400
	s_add_i32 s3, s3, 0
	global_load_lds_dwordx4 v[12:13], off
	s_mov_b32 m0, s10
	v_mov_b32_e32 v5, v1
	global_load_lds_dwordx4 v[2:3], off
	v_lshl_add_u64 v[2:3], v[4:5], 1, s[50:51]
	s_mov_b32 m0, s3
	v_mov_b32_e32 v7, v1
	s_add_i32 s11, s3, 0x400
	global_load_lds_dwordx4 v[2:3], off
	v_lshl_add_u64 v[2:3], v[6:7], 1, s[50:51]
	s_mov_b32 m0, s11
	v_mov_b32_e32 v9, v1
	s_add_i32 s12, s3, 0x800
	global_load_lds_dwordx4 v[2:3], off
	v_lshl_add_u64 v[2:3], v[8:9], 1, s[50:51]
	s_mov_b32 m0, s12
	v_mov_b32_e32 v11, v1
	s_add_i32 s20, s3, 0xc00
	v_and_b32_e32 v210, 31, v14
	v_bfe_u32 v237, v14, 5, 1
	s_lshl_b32 s1, s29, 5
	global_load_lds_dwordx4 v[2:3], off
	v_lshl_add_u64 v[2:3], v[10:11], 1, s[50:51]
	s_mov_b32 m0, s20
	v_or_b32_e32 v0, s1, v210
	global_load_lds_dwordx4 v[2:3], off
	v_lshlrev_b32_e32 v2, 3, v237
	v_lshl_or_b32 v0, v0, 11, v2
	v_lshl_add_u64 v[2:3], v[0:1], 1, s[4:5]
	global_load_dwordx4 v[178:181], v[2:3], off
	global_load_dwordx4 v[182:185], v[2:3], off offset:32
	global_load_dwordx4 v[186:189], v[2:3], off offset:64
	global_load_dwordx4 v[190:193], v[2:3], off offset:96
	global_load_dwordx4 v[194:197], v[2:3], off offset:128
	global_load_dwordx4 v[198:201], v[2:3], off offset:160
	global_load_dwordx4 v[202:205], v[2:3], off offset:192
	global_load_dwordx4 v[206:209], v[2:3], off offset:224
	s_and_b32 s4, s21, 0x3fffffc0
	s_lshl_b32 s4, s4, 2
	v_and_b32_e32 v15, 63, v14
	s_add_i32 s21, s4, 0
	v_lshlrev_b32_e32 v3, 4, v14
	s_add_i32 s23, s1, s25
	s_addk_i32 s25, 0x100
	s_add_i32 s21, s21, 0x18000
	v_lshlrev_b32_e32 v2, 3, v15
	v_and_b32_e32 v3, 0xc0, v3
	v_lshlrev_b32_e32 v4, 1, v14
	s_lshr_b32 s25, s25, 6
	v_lshlrev_b32_e32 v211, 2, v237
	v_and_or_b32 v3, v2, 24, v3
	v_and_b32_e32 v4, 32, v4
	v_and_b32_e32 v2, 0x100, v2
	s_cmp_lg_u32 0, -1
	v_sub_u32_e32 v0, v210, v211
	v_or3_b32 v2, v3, v4, v2
	s_cselect_b32 s4, 0, 0
	v_add_u32_e32 v245, s23, v0
	v_add_u32_e32 v246, s4, v2
	v_lshlrev_b32_e32 v0, 8, v210
	v_bitop3_b32 v2, v237, v14, 7 bitop3:0x78
	s_lshl_b32 s29, s29, 15
	v_lshl_or_b32 v248, v2, 4, v0
	v_lshl_or_b32 v2, v18, 12, s29
	v_or_b32_e32 v0, v2, v19
	s_movk_i32 s29, 0x4000
	v_lshl_add_u64 v[212:213], v[0:1], 1, s[56:57]
	v_or3_b32 v0, v2, v20, s29
	v_lshl_add_u64 v[216:217], v[0:1], 1, s[56:57]
	v_lshlrev_b32_e32 v0, 11, v14
	v_lshlrev_b32_e32 v2, 12, v21
	s_mov_b32 s29, 0x8000
	v_and_or_b32 v0, v0, s29, v2
	v_add_u32_e32 v0, s33, v0
	v_or3_b32 v0, v0, v23, v22
	v_or_b32_e32 v2, 64, v0
	v_mov_b32_e32 v3, v1
	s_waitcnt vmcnt(0)
	v_cmp_gt_u32_e64 s[4:5], 32, v15
	v_lshlrev_b64 v[218:219], 1, v[0:1]
	v_lshlrev_b64 v[220:221], 1, v[2:3]
	v_add_u32_e32 v2, 0x4000, v0
	v_add_u32_e32 v0, 0x4040, v0
	v_mov_b32_e32 v14, v1
	v_mov_b32_e32 v15, v1
	v_lshlrev_b64 v[222:223], 1, v[2:3]
	v_lshlrev_b64 v[224:225], 1, v[0:1]
	v_mov_b32_e32 v0, v1
	v_mov_b32_e32 v2, v1
	v_mov_b32_e32 v4, v1
	v_mov_b32_e32 v6, v1
	v_mov_b32_e32 v8, v1
	v_mov_b32_e32 v10, v1
	v_mov_b32_e32 v12, v1
	v_mov_b32_e32 v13, v1
	v_mov_b64_e32 v[144:145], v[14:15]
	v_mov_b64_e32 v[128:129], v[14:15]
	v_mov_b64_e32 v[112:113], v[14:15]
	v_mov_b64_e32 v[96:97], v[14:15]
	v_mov_b64_e32 v[80:81], v[14:15]
	v_mov_b64_e32 v[64:65], v[14:15]
	v_mov_b64_e32 v[48:49], v[14:15]
	v_mov_b64_e32 v[32:33], v[14:15]
	s_mov_b32 s22, 2
	s_or_b32 s28, s23, 31
	v_lshl_add_u32 v247, v210, 2, s21
	v_mov_b32_e32 v249, 0xf149f2ca
	v_mov_b32_e32 v250, 0
	s_movk_i32 s29, 0x7f
	s_mov_b64 s[56:57], s[52:53]
	v_mov_b64_e32 v[142:143], v[12:13]
	v_mov_b64_e32 v[140:141], v[10:11]
	v_mov_b64_e32 v[138:139], v[8:9]
	v_mov_b64_e32 v[136:137], v[6:7]
	v_mov_b64_e32 v[134:135], v[4:5]
	v_mov_b64_e32 v[132:133], v[2:3]
	v_mov_b64_e32 v[130:131], v[0:1]
	v_mov_b64_e32 v[126:127], v[12:13]
	v_mov_b64_e32 v[124:125], v[10:11]
	v_mov_b64_e32 v[122:123], v[8:9]
	v_mov_b64_e32 v[120:121], v[6:7]
	v_mov_b64_e32 v[118:119], v[4:5]
	v_mov_b64_e32 v[116:117], v[2:3]
	v_mov_b64_e32 v[114:115], v[0:1]
	v_mov_b64_e32 v[110:111], v[12:13]
	v_mov_b64_e32 v[108:109], v[10:11]
	v_mov_b64_e32 v[106:107], v[8:9]
	v_mov_b64_e32 v[104:105], v[6:7]
	v_mov_b64_e32 v[102:103], v[4:5]
	v_mov_b64_e32 v[100:101], v[2:3]
	v_mov_b64_e32 v[98:99], v[0:1]
	v_mov_b64_e32 v[94:95], v[12:13]
	v_mov_b64_e32 v[92:93], v[10:11]
	v_mov_b64_e32 v[90:91], v[8:9]
	v_mov_b64_e32 v[88:89], v[6:7]
	v_mov_b64_e32 v[86:87], v[4:5]
	v_mov_b64_e32 v[84:85], v[2:3]
	v_mov_b64_e32 v[82:83], v[0:1]
	v_mov_b64_e32 v[78:79], v[12:13]
	v_mov_b64_e32 v[76:77], v[10:11]
	v_mov_b64_e32 v[74:75], v[8:9]
	v_mov_b64_e32 v[72:73], v[6:7]
	v_mov_b64_e32 v[70:71], v[4:5]
	v_mov_b64_e32 v[68:69], v[2:3]
	v_mov_b64_e32 v[66:67], v[0:1]
	v_mov_b64_e32 v[62:63], v[12:13]
	v_mov_b64_e32 v[60:61], v[10:11]
	v_mov_b64_e32 v[58:59], v[8:9]
	v_mov_b64_e32 v[56:57], v[6:7]
	v_mov_b64_e32 v[54:55], v[4:5]
	v_mov_b64_e32 v[52:53], v[2:3]
	v_mov_b64_e32 v[50:51], v[0:1]
	v_mov_b64_e32 v[46:47], v[12:13]
	v_mov_b64_e32 v[44:45], v[10:11]
	v_mov_b64_e32 v[42:43], v[8:9]
	v_mov_b64_e32 v[40:41], v[6:7]
	v_mov_b64_e32 v[38:39], v[4:5]
	v_mov_b64_e32 v[36:37], v[2:3]
	v_mov_b64_e32 v[34:35], v[0:1]
	v_mov_b64_e32 v[30:31], v[12:13]
	v_mov_b64_e32 v[28:29], v[10:11]
	v_mov_b64_e32 v[26:27], v[8:9]
	v_mov_b64_e32 v[24:25], v[6:7]
	v_mov_b64_e32 v[22:23], v[4:5]
	v_mov_b64_e32 v[20:21], v[2:3]
	v_mov_b64_e32 v[18:19], v[0:1]
	s_waitcnt vmcnt(0) lgkmcnt(0)
	s_barrier
	v_readlane_b32 s33, v255, 11
	s_nop 3
	s_cmp_lt_u32 s33, 0x100
	s_cbranch_scc1 .Lda_h0_go
	s_barrier
.Lda_h0_go:
	s_branch .LBB0_427
.Lda_skip1:
	s_waitcnt vmcnt(0)
	s_barrier
	s_add_i32 s33, s22, -1
	s_cmp_ge_u32 s33, s25
	s_cbranch_scc1 .LBB0_437
	v_lshl_add_u64 v[150:151], v[230:231], 0, s[26:27]
	s_add_i32 m0, s3, 0x8000
	s_nop 0
	global_load_lds_dwordx4 v[150:151], off
	v_lshl_add_u64 v[150:151], v[228:229], 0, s[26:27]
	s_add_i32 m0, s3, 0x8400
	s_nop 0
	global_load_lds_dwordx4 v[150:151], off
	v_lshl_add_u64 v[150:151], v[226:227], 0, s[26:27]
	s_add_i32 m0, s3, 0x8800
	s_nop 0
	global_load_lds_dwordx4 v[150:151], off
	v_lshl_add_u64 v[150:151], v[14:15], 0, s[26:27]
	s_add_i32 m0, s3, 0x8c00
	s_nop 0
	global_load_lds_dwordx4 v[150:151], off
	s_branch .LBB0_437
.Lda_skip2:
	s_waitcnt vmcnt(0)
	s_barrier
	s_and_b64 vcc, exec, s[58:59]
	s_cbranch_vccnz .LBB0_426
	v_lshl_add_u64 v[150:151], s[56:57], 0, v[218:219]
	v_lshl_add_u64 v[150:151], v[150:151], 0, s[34:35]
	s_mov_b32 m0, s3
	s_nop 0
	global_load_lds_dwordx4 v[150:151], off
	v_lshl_add_u64 v[150:151], s[56:57], 0, v[220:221]
	v_lshl_add_u64 v[150:151], v[150:151], 0, s[34:35]
	s_mov_b32 m0, s11
	s_nop 0
	global_load_lds_dwordx4 v[150:151], off
	v_lshl_add_u64 v[150:151], s[56:57], 0, v[222:223]
	v_lshl_add_u64 v[150:151], v[150:151], 0, s[34:35]
	s_mov_b32 m0, s12
	s_nop 0
	global_load_lds_dwordx4 v[150:151], off
	v_lshl_add_u64 v[150:151], s[56:57], 0, v[224:225]
	v_lshl_add_u64 v[150:151], v[150:151], 0, s[34:35]
	s_mov_b32 m0, s20
	s_nop 0
	global_load_lds_dwordx4 v[150:151], off
	s_branch .LBB0_426

.LBB0_425:
	s_waitcnt vmcnt(0)
	s_barrier
	s_and_b64 vcc, exec, s[58:59]
	s_cbranch_vccnz .Lda_nov2
	v_lshl_add_u64 v[150:151], s[56:57], 0, v[218:219]
	v_lshl_add_u64 v[150:151], v[150:151], 0, s[34:35]
	s_mov_b32 m0, s3
	s_nop 0
	global_load_lds_dwordx4 v[150:151], off
	v_lshl_add_u64 v[150:151], s[56:57], 0, v[220:221]
	v_lshl_add_u64 v[150:151], v[150:151], 0, s[34:35]
	s_mov_b32 m0, s11
	s_nop 0
	global_load_lds_dwordx4 v[150:151], off
	v_lshl_add_u64 v[150:151], s[56:57], 0, v[222:223]
	v_lshl_add_u64 v[150:151], v[150:151], 0, s[34:35]
	s_mov_b32 m0, s12
	s_nop 0
	global_load_lds_dwordx4 v[150:151], off
	v_lshl_add_u64 v[150:151], s[56:57], 0, v[224:225]
	v_lshl_add_u64 v[150:151], v[150:151], 0, s[34:35]
	s_mov_b32 m0, s20
	s_nop 0
	global_load_lds_dwordx4 v[150:151], off

.LBB0_427:
	s_add_i32 s33, s22, -1
	s_cmp_ge_u32 s33, s25
	v_lshl_add_u64 v[234:235], s[56:57], 0, v[212:213]
	v_lshl_add_u64 v[232:233], s[56:57], 0, v[216:217]
	v_lshl_add_u64 v[230:231], s[56:57], 0, v[218:219]
	v_lshl_add_u64 v[228:229], s[56:57], 0, v[220:221]
	v_lshl_add_u64 v[226:227], s[56:57], 0, v[222:223]
	v_lshl_add_u64 v[14:15], s[56:57], 0, v[224:225]
	s_cbranch_scc1 .LBB0_429
	v_lshl_add_u64 v[2:3], v[234:235], 0, s[18:19]
	s_add_i32 m0, s0, 0x14000
	s_nop 0
	global_load_lds_dwordx4 v[2:3], off
	v_lshl_add_u64 v[2:3], v[232:233], 0, s[18:19]
	s_add_i32 m0, s0, 0x14400
	s_nop 0
	global_load_lds_dwordx4 v[2:3], off
.LBB0_429:
	s_add_i32 s33, s29, 0xffffff81
	s_cmp_gt_i32 s33, s28
	s_cbranch_scc1 .Lda_skip1
	s_add_i32 s33, 0, 0x10000
	s_cmp_lg_u32 s33, -1
	v_mov_b32_e32 v0, v248
	s_cselect_b32 s33, s33, 0
	s_nop 0
	v_add_u32_e32 v251, s33, v0
	ds_read_b128 v[2:5], v251 offset:0
	ds_read_b128 v[6:9], v251 offset:0x2000
	v_xad_u32 v252, v0, 32, s33
	ds_read_b128 v[10:13], v252 offset:0
	ds_read_b128 v[240:243], v252 offset:0x2000
	s_waitcnt lgkmcnt(2)
	v_xad_u32 v253, v0, 64, s33
	v_xor_b32_e32 v0, 0x60, v0
	v_add_u32_e32 v0, s33, v0
	v_mfma_f32_32x32x16_bf16 v[162:177], v[2:5], v[178:181], 0
	v_mfma_f32_32x32x16_bf16 v[146:161], v[6:9], v[178:181], 0
	ds_read_b128 v[2:5], v253 offset:0
	ds_read_b128 v[6:9], v253 offset:0x2000
	s_waitcnt lgkmcnt(2)
	v_mfma_f32_32x32x16_bf16 v[162:177], v[10:13], v[182:185], v[162:177]
	v_mfma_f32_32x32x16_bf16 v[146:161], v[240:243], v[182:185], v[146:161]
	ds_read_b128 v[10:13], v0 offset:0
	ds_read_b128 v[240:243], v0 offset:0x2000
	s_waitcnt lgkmcnt(2)
	v_mfma_f32_32x32x16_bf16 v[162:177], v[2:5], v[186:189], v[162:177]
	v_mfma_f32_32x32x16_bf16 v[146:161], v[6:9], v[186:189], v[146:161]
	ds_read_b128 v[2:5], v251 offset:0x80
	ds_read_b128 v[6:9], v251 offset:0x2080
	s_waitcnt lgkmcnt(2)
	v_mfma_f32_32x32x16_bf16 v[162:177], v[10:13], v[190:193], v[162:177]
	v_mfma_f32_32x32x16_bf16 v[146:161], v[240:243], v[190:193], v[146:161]
	ds_read_b128 v[10:13], v252 offset:0x80
	ds_read_b128 v[240:243], v252 offset:0x2080
	s_waitcnt lgkmcnt(2)
	v_mfma_f32_32x32x16_bf16 v[162:177], v[2:5], v[194:197], v[162:177]
	v_mfma_f32_32x32x16_bf16 v[146:161], v[6:9], v[194:197], v[146:161]
	ds_read_b128 v[2:5], v253 offset:0x80
	ds_read_b128 v[6:9], v253 offset:0x2080
	s_waitcnt lgkmcnt(2)
	v_mfma_f32_32x32x16_bf16 v[162:177], v[10:13], v[198:201], v[162:177]
	v_mfma_f32_32x32x16_bf16 v[146:161], v[240:243], v[198:201], v[146:161]
	ds_read_b128 v[10:13], v0 offset:0x80
	ds_read_b128 v[240:243], v0 offset:0x2080
	s_waitcnt lgkmcnt(2)
	v_mfma_f32_32x32x16_bf16 v[162:177], v[2:5], v[202:205], v[162:177]
	v_mfma_f32_32x32x16_bf16 v[146:161], v[6:9], v[202:205], v[146:161]
	s_waitcnt lgkmcnt(0)
	v_mfma_f32_32x32x16_bf16 v[162:177], v[10:13], v[206:209], v[162:177]
	v_mfma_f32_32x32x16_bf16 v[146:161], v[240:243], v[206:209], v[146:161]
	s_sub_i32 s33, s29, 64
	s_cmp_le_i32 s33, s23
	s_cbranch_scc1 .LBB0_432
	v_mov_b32_e32 v0, v245
	s_nop 0
	v_cmp_gt_u32_e32 vcc, s96, v0
	v_subrev_u32_e32 v2, 32, v0
	s_nop 3
	v_cndmask_b32_e32 v162, v16, v162, vcc
	v_cmp_gt_u32_e32 vcc, s96, v2
	v_subrev_u32_e32 v2, 33, v0
	s_nop 0
	v_cndmask_b32_e32 v146, v16, v146, vcc
	v_cmp_lt_i32_e32 vcc, 0, v0
	s_nop 1
	v_cndmask_b32_e32 v163, v16, v163, vcc
	v_cmp_gt_u32_e32 vcc, s96, v2
	v_add_u32_e32 v2, -2, v0
	s_nop 0
	v_cndmask_b32_e32 v147, v16, v147, vcc
	v_cmp_gt_u32_e32 vcc, s96, v2
	v_subrev_u32_e32 v2, 34, v0
	s_nop 0
	v_cndmask_b32_e32 v164, v16, v164, vcc
	v_cmp_gt_u32_e32 vcc, s96, v2
	v_add_u32_e32 v2, -3, v0
	s_nop 0
	v_cndmask_b32_e32 v148, v16, v148, vcc
	v_cmp_gt_u32_e32 vcc, s96, v2
	v_subrev_u32_e32 v2, 35, v0
	s_nop 0
	v_cndmask_b32_e32 v165, v16, v165, vcc
	v_cmp_gt_u32_e32 vcc, s96, v2
	v_add_u32_e32 v2, -8, v0
	s_nop 0
	v_cndmask_b32_e32 v149, v16, v149, vcc
	v_cmp_gt_u32_e32 vcc, s96, v2
	v_subrev_u32_e32 v2, 40, v0
	s_nop 0
	v_cndmask_b32_e32 v166, v16, v166, vcc
	v_cmp_gt_u32_e32 vcc, s96, v2
	v_add_u32_e32 v2, -9, v0
	s_nop 0
	v_cndmask_b32_e32 v150, v16, v150, vcc
	v_cmp_gt_u32_e32 vcc, s96, v2
	v_subrev_u32_e32 v2, 41, v0
	s_nop 0
	v_cndmask_b32_e32 v167, v16, v167, vcc
	v_cmp_gt_u32_e32 vcc, s96, v2
	v_add_u32_e32 v2, -10, v0
	s_nop 0
	v_cndmask_b32_e32 v151, v16, v151, vcc
	v_cmp_gt_u32_e32 vcc, s96, v2
	v_subrev_u32_e32 v2, 42, v0
	s_nop 0
	v_cndmask_b32_e32 v168, v16, v168, vcc
	v_cmp_gt_u32_e32 vcc, s96, v2
	v_add_u32_e32 v2, -11, v0
	s_nop 0
	v_cndmask_b32_e32 v152, v16, v152, vcc
	v_cmp_gt_u32_e32 vcc, s96, v2
	v_subrev_u32_e32 v2, 43, v0
	s_nop 0
	v_cndmask_b32_e32 v169, v16, v169, vcc
	v_cmp_gt_u32_e32 vcc, s96, v2
	v_add_u32_e32 v2, -16, v0
	s_nop 0
	v_cndmask_b32_e32 v153, v16, v153, vcc
	v_cmp_gt_u32_e32 vcc, s96, v2
	v_subrev_u32_e32 v2, 48, v0
	s_nop 0
	v_cndmask_b32_e32 v170, v16, v170, vcc
	v_cmp_gt_u32_e32 vcc, s96, v2
	v_subrev_u32_e32 v2, 17, v0
	s_nop 0
	v_cndmask_b32_e32 v154, v16, v154, vcc
	v_cmp_gt_u32_e32 vcc, s96, v2
	v_subrev_u32_e32 v2, 49, v0
	s_nop 0
	v_cndmask_b32_e32 v171, v16, v171, vcc
	v_cmp_gt_u32_e32 vcc, s96, v2
	v_subrev_u32_e32 v2, 18, v0
	s_nop 0
	v_cndmask_b32_e32 v155, v16, v155, vcc
	v_cmp_gt_u32_e32 vcc, s96, v2
	v_subrev_u32_e32 v2, 50, v0
	s_nop 0
	v_cndmask_b32_e32 v172, v16, v172, vcc
	v_cmp_gt_u32_e32 vcc, s96, v2
	v_subrev_u32_e32 v2, 19, v0
	s_nop 0
	v_cndmask_b32_e32 v156, v16, v156, vcc
	v_cmp_gt_u32_e32 vcc, s96, v2
	v_subrev_u32_e32 v2, 51, v0
	s_nop 0
	v_cndmask_b32_e32 v173, v16, v173, vcc
	v_cmp_gt_u32_e32 vcc, s96, v2
	v_subrev_u32_e32 v2, 24, v0
	s_nop 0
	v_cndmask_b32_e32 v157, v16, v157, vcc
	v_cmp_gt_u32_e32 vcc, s96, v2
	v_subrev_u32_e32 v2, 56, v0
	s_nop 0
	v_cndmask_b32_e32 v174, v16, v174, vcc
	v_cmp_gt_u32_e32 vcc, s96, v2
	v_subrev_u32_e32 v2, 25, v0
	s_nop 0
	v_cndmask_b32_e32 v158, v16, v158, vcc
	v_cmp_gt_u32_e32 vcc, s96, v2
	v_subrev_u32_e32 v2, 57, v0
	s_nop 0
	v_cndmask_b32_e32 v175, v16, v175, vcc
	v_cmp_gt_u32_e32 vcc, s96, v2
	v_subrev_u32_e32 v2, 26, v0
	s_nop 0
	v_cndmask_b32_e32 v159, v16, v159, vcc
	v_cmp_gt_u32_e32 vcc, s96, v2
	v_subrev_u32_e32 v2, 58, v0
	s_nop 0
	v_cndmask_b32_e32 v176, v16, v176, vcc
	v_cmp_gt_u32_e32 vcc, s96, v2
	v_subrev_u32_e32 v2, 27, v0
	v_subrev_u32_e32 v0, 59, v0
	v_cndmask_b32_e32 v160, v16, v160, vcc
	v_cmp_gt_u32_e32 vcc, s96, v2
	s_nop 1
	v_cndmask_b32_e32 v177, v16, v177, vcc
	v_cmp_gt_u32_e32 vcc, s96, v0
	s_nop 1
	v_cndmask_b32_e32 v161, v16, v161, vcc

.LBB0_436:
	s_waitcnt vmcnt(0)
	s_barrier
	s_add_i32 s33, s22, -1
	s_cmp_ge_u32 s33, s25
	s_cbranch_scc1 .Lda_nov1
	v_lshl_add_u64 v[150:151], v[230:231], 0, s[26:27]
	s_add_i32 m0, s3, 0x8000
	s_nop 0
	global_load_lds_dwordx4 v[150:151], off
	v_lshl_add_u64 v[150:151], v[228:229], 0, s[26:27]
	s_add_i32 m0, s3, 0x8400
	s_nop 0
	global_load_lds_dwordx4 v[150:151], off
	v_lshl_add_u64 v[150:151], v[226:227], 0, s[26:27]
	s_add_i32 m0, s3, 0x8800
	s_nop 0
	global_load_lds_dwordx4 v[150:151], off
	v_lshl_add_u64 v[150:151], v[14:15], 0, s[26:27]
	s_add_i32 m0, s3, 0x8c00
	s_nop 0
	global_load_lds_dwordx4 v[150:151], off

.LBB0_437:
	s_waitcnt vmcnt(0)
	s_cmp_ge_u32 s22, s25
	s_cselect_b64 s[58:59], -1, 0
	s_and_b64 vcc, exec, s[58:59]
	s_waitcnt vmcnt(0) lgkmcnt(0)
	s_barrier
	s_cbranch_vccnz .LBB0_439
	s_mov_b32 m0, s2
	v_lshl_add_u64 v[2:3], v[234:235], 0, s[30:31]
	global_load_lds_dwordx4 v[2:3], off
	v_lshl_add_u64 v[2:3], v[232:233], 0, s[30:31]
	s_mov_b32 m0, s10
	s_nop 0
	global_load_lds_dwordx4 v[2:3], off
.LBB0_439:
	s_sub_i32 s33, s29, 63
	s_cmp_gt_i32 s33, s28
	s_cbranch_scc1 .Lda_skip2
	s_cmp_lg_u32 0, -1
	s_cselect_b32 s33, 0, 0
	v_mov_b32_e32 v0, v248
	s_add_i32 s33, s33, 0x14000
	s_nop 0
	v_add_u32_e32 v14, s33, v0
	ds_read_b128 v[2:5], v14 offset:0
	ds_read_b128 v[6:9], v14 offset:0x2000
	v_xad_u32 v15, v0, 32, s33
	ds_read_b128 v[10:13], v15 offset:0
	ds_read_b128 v[226:229], v15 offset:0x2000
	s_waitcnt lgkmcnt(2)
	v_xad_u32 v230, v0, 64, s33
	v_xor_b32_e32 v0, 0x60, v0
	v_add_u32_e32 v0, s33, v0
	v_mfma_f32_32x32x16_bf16 v[162:177], v[2:5], v[178:181], 0
	v_mfma_f32_32x32x16_bf16 v[146:161], v[6:9], v[178:181], 0
	ds_read_b128 v[2:5], v230 offset:0
	ds_read_b128 v[6:9], v230 offset:0x2000
	s_waitcnt lgkmcnt(2)
	v_mfma_f32_32x32x16_bf16 v[162:177], v[10:13], v[182:185], v[162:177]
	v_mfma_f32_32x32x16_bf16 v[146:161], v[226:229], v[182:185], v[146:161]
	ds_read_b128 v[10:13], v0 offset:0
	ds_read_b128 v[226:229], v0 offset:0x2000
	s_waitcnt lgkmcnt(2)
	v_mfma_f32_32x32x16_bf16 v[162:177], v[2:5], v[186:189], v[162:177]
	v_mfma_f32_32x32x16_bf16 v[146:161], v[6:9], v[186:189], v[146:161]
	ds_read_b128 v[2:5], v14 offset:0x80
	ds_read_b128 v[6:9], v14 offset:0x2080
	s_waitcnt lgkmcnt(2)
	v_mfma_f32_32x32x16_bf16 v[162:177], v[10:13], v[190:193], v[162:177]
	v_mfma_f32_32x32x16_bf16 v[146:161], v[226:229], v[190:193], v[146:161]
	ds_read_b128 v[10:13], v15 offset:0x80
	ds_read_b128 v[226:229], v15 offset:0x2080
	s_waitcnt lgkmcnt(2)
	v_mfma_f32_32x32x16_bf16 v[162:177], v[2:5], v[194:197], v[162:177]
	v_mfma_f32_32x32x16_bf16 v[146:161], v[6:9], v[194:197], v[146:161]
	ds_read_b128 v[2:5], v230 offset:0x80
	ds_read_b128 v[6:9], v230 offset:0x2080
	s_waitcnt lgkmcnt(2)
	v_mfma_f32_32x32x16_bf16 v[162:177], v[10:13], v[198:201], v[162:177]
	v_mfma_f32_32x32x16_bf16 v[146:161], v[226:229], v[198:201], v[146:161]
	ds_read_b128 v[10:13], v0 offset:0x80
	ds_read_b128 v[226:229], v0 offset:0x2080
	s_waitcnt lgkmcnt(2)
	v_mfma_f32_32x32x16_bf16 v[162:177], v[2:5], v[202:205], v[162:177]
	v_mfma_f32_32x32x16_bf16 v[146:161], v[6:9], v[202:205], v[146:161]
	s_waitcnt lgkmcnt(0)
	v_mfma_f32_32x32x16_bf16 v[162:177], v[10:13], v[206:209], v[162:177]
	v_mfma_f32_32x32x16_bf16 v[146:161], v[226:229], v[206:209], v[146:161]
	s_cmp_le_i32 s29, s23
	s_cbranch_scc1 .LBB0_442
	v_subrev_u32_e32 v0, 64, v245
	s_nop 0
	v_cmp_gt_u32_e32 vcc, s96, v0
	v_subrev_u32_e32 v2, 32, v0
	s_nop 4
	v_cndmask_b32_e32 v162, v16, v162, vcc
	v_cmp_gt_u32_e32 vcc, s96, v2
	v_subrev_u32_e32 v2, 33, v0
	s_nop 0
	v_cndmask_b32_e32 v146, v16, v146, vcc
	v_cmp_lt_i32_e32 vcc, 0, v0
	s_nop 1
	v_cndmask_b32_e32 v163, v16, v163, vcc
	v_cmp_gt_u32_e32 vcc, s96, v2
	v_add_u32_e32 v2, -2, v0
	s_nop 0
	v_cndmask_b32_e32 v147, v16, v147, vcc
	v_cmp_gt_u32_e32 vcc, s96, v2
	v_subrev_u32_e32 v2, 34, v0
	s_nop 0
	v_cndmask_b32_e32 v164, v16, v164, vcc
	v_cmp_gt_u32_e32 vcc, s96, v2
	v_add_u32_e32 v2, -3, v0
	s_nop 0
	v_cndmask_b32_e32 v148, v16, v148, vcc
	v_cmp_gt_u32_e32 vcc, s96, v2
	v_subrev_u32_e32 v2, 35, v0
	s_nop 0
	v_cndmask_b32_e32 v165, v16, v165, vcc
	v_cmp_gt_u32_e32 vcc, s96, v2
	v_add_u32_e32 v2, -8, v0
	s_nop 0
	v_cndmask_b32_e32 v149, v16, v149, vcc
	v_cmp_gt_u32_e32 vcc, s96, v2
	v_subrev_u32_e32 v2, 40, v0
	s_nop 0
	v_cndmask_b32_e32 v166, v16, v166, vcc
	v_cmp_gt_u32_e32 vcc, s96, v2
	v_add_u32_e32 v2, -9, v0
	s_nop 0
	v_cndmask_b32_e32 v150, v16, v150, vcc
	v_cmp_gt_u32_e32 vcc, s96, v2
	v_subrev_u32_e32 v2, 41, v0
	s_nop 0
	v_cndmask_b32_e32 v167, v16, v167, vcc
	v_cmp_gt_u32_e32 vcc, s96, v2
	v_add_u32_e32 v2, -10, v0
	s_nop 0
	v_cndmask_b32_e32 v151, v16, v151, vcc
	v_cmp_gt_u32_e32 vcc, s96, v2
	v_subrev_u32_e32 v2, 42, v0
	s_nop 0
	v_cndmask_b32_e32 v168, v16, v168, vcc
	v_cmp_gt_u32_e32 vcc, s96, v2
	v_add_u32_e32 v2, -11, v0
	s_nop 0
	v_cndmask_b32_e32 v152, v16, v152, vcc
	v_cmp_gt_u32_e32 vcc, s96, v2
	v_subrev_u32_e32 v2, 43, v0
	s_nop 0
	v_cndmask_b32_e32 v169, v16, v169, vcc
	v_cmp_gt_u32_e32 vcc, s96, v2
	v_add_u32_e32 v2, -16, v0
	s_nop 0
	v_cndmask_b32_e32 v153, v16, v153, vcc
	v_cmp_gt_u32_e32 vcc, s96, v2
	v_subrev_u32_e32 v2, 48, v0
	s_nop 0
	v_cndmask_b32_e32 v170, v16, v170, vcc
	v_cmp_gt_u32_e32 vcc, s96, v2
	v_subrev_u32_e32 v2, 17, v0
	s_nop 0
	v_cndmask_b32_e32 v154, v16, v154, vcc
	v_cmp_gt_u32_e32 vcc, s96, v2
	v_subrev_u32_e32 v2, 49, v0
	s_nop 0
	v_cndmask_b32_e32 v171, v16, v171, vcc
	v_cmp_gt_u32_e32 vcc, s96, v2
	v_subrev_u32_e32 v2, 18, v0
	s_nop 0
	v_cndmask_b32_e32 v155, v16, v155, vcc
	v_cmp_gt_u32_e32 vcc, s96, v2
	v_subrev_u32_e32 v2, 50, v0
	s_nop 0
	v_cndmask_b32_e32 v172, v16, v172, vcc
	v_cmp_gt_u32_e32 vcc, s96, v2
	v_subrev_u32_e32 v2, 19, v0
	s_nop 0
	v_cndmask_b32_e32 v156, v16, v156, vcc
	v_cmp_gt_u32_e32 vcc, s96, v2
	v_subrev_u32_e32 v2, 51, v0
	s_nop 0
	v_cndmask_b32_e32 v173, v16, v173, vcc
	v_cmp_gt_u32_e32 vcc, s96, v2
	v_subrev_u32_e32 v2, 24, v0
	s_nop 0
	v_cndmask_b32_e32 v157, v16, v157, vcc
	v_cmp_gt_u32_e32 vcc, s96, v2
	v_subrev_u32_e32 v2, 56, v0
	s_nop 0
	v_cndmask_b32_e32 v174, v16, v174, vcc
	v_cmp_gt_u32_e32 vcc, s96, v2
	v_subrev_u32_e32 v2, 25, v0
	s_nop 0
	v_cndmask_b32_e32 v158, v16, v158, vcc
	v_cmp_gt_u32_e32 vcc, s96, v2
	v_subrev_u32_e32 v2, 57, v0
	s_nop 0
	v_cndmask_b32_e32 v175, v16, v175, vcc
	v_cmp_gt_u32_e32 vcc, s96, v2
	v_subrev_u32_e32 v2, 26, v0
	s_nop 0
	v_cndmask_b32_e32 v159, v16, v159, vcc
	v_cmp_gt_u32_e32 vcc, s96, v2
	v_subrev_u32_e32 v2, 58, v0
	s_nop 0
	v_cndmask_b32_e32 v176, v16, v176, vcc
	v_cmp_gt_u32_e32 vcc, s96, v2
	v_subrev_u32_e32 v2, 27, v0
	v_subrev_u32_e32 v0, 59, v0
	v_cndmask_b32_e32 v160, v16, v160, vcc
	v_cmp_gt_u32_e32 vcc, s96, v2
	s_nop 1
	v_cndmask_b32_e32 v177, v16, v177, vcc
	v_cmp_gt_u32_e32 vcc, s96, v0
	s_nop 1
	v_cndmask_b32_e32 v161, v16, v161, vcc

.LBB0_445:
	v_readlane_b32 s33, v255, 11
	s_nop 3
	s_cmp_ge_u32 s33, 0x100
	s_cbranch_scc1 .Lda_exit_h1
	s_barrier
